# GEMM prologues: K-tile 1 half-tile loads issued together with K-tile 0 (first wait vmcnt(8) moved behind them)
# speedup vs baseline: 1.0017x; 1.0010x over previous
.LBB0_23:
	s_lshr_b32 s19, s90, 6
	s_and_b32 s19, s19, 3
	s_mul_i32 s36, s19, 0xfe
	s_add_i32 s19, s94, 0x18000
	s_lshr_b32 s24, s90, 3
	s_and_b32 s5, s5, 3
	v_and_b32_e32 v134, 15, v14
	v_and_b32_e32 v135, 48, v14
	v_lshlrev_b32_e32 v14, 2, v14
	v_lshl_add_u64 v[6:7], v[6:7], 0, s[34:35]
	s_mov_b32 m0, s19
	s_add_i32 s30, s94, 0x1a000
	v_lshl_or_b32 v15, v134, 6, v135
	v_and_b32_e32 v14, 32, v14
	s_lshl_b32 s26, s93, 13
	s_lshl_b32 s27, s5, 12
	s_and_b32 s37, s24, 7
	global_load_lds_dwordx4 v[6:7], off
	v_lshl_add_u64 v[4:5], v[4:5], 0, s[34:35]
	s_mov_b32 m0, s30
	s_add_i32 s61, s94, 0x8000
	s_add_i32 s62, s94, 0xa000
	v_bitop3_b32 v137, v15, s26, v14 bitop3:0xde
	global_load_lds_dwordx4 v[4:5], off
	v_lshl_add_u64 v[0:1], v[0:1], 0, s[34:35]
	s_mov_b32 m0, s61
	s_add_u32 s26, s84, 0x40080
	v_bitop3_b32 v16, v15, s27, v14 bitop3:0xde
	global_load_lds_dwordx4 v[0:1], off
	v_lshl_add_u64 v[0:1], v[2:3], 0, s[34:35]
	s_mov_b32 m0, s62
	s_addc_u32 s27, s85, 0
	s_add_i32 s63, s94, 0x1c000
	global_load_lds_dwordx4 v[0:1], off
	v_lshl_add_u64 v[0:1], s[26:27], 0, v[168:169]
	s_mov_b32 m0, s63
	s_add_i32 s24, s94, 0x1e000
	global_load_lds_dwordx4 v[0:1], off
	v_lshl_add_u64 v[0:1], s[26:27], 0, v[128:129]
	s_mov_b32 m0, s24
	s_mul_i32 s26, s15, 0x3f8
	global_load_lds_dwordx4 v[0:1], off
	s_waitcnt vmcnt(8)
	s_barrier
	s_add_i32 s26, s26, s36
	s_add_i32 s26, s26, -2
	s_ashr_i32 s27, s26, 31
	s_lshl_b64 s[26:27], s[26:27], 11
	v_lshlrev_b32_e32 v0, 14, v8
	s_add_u32 s96, s74, s26
	v_and_b32_e32 v0, 0xffff8000, v0
	s_addc_u32 s97, s75, s27
	v_lshl_add_u32 v0, v10, 11, v0
	v_and_b32_e32 v1, 1, v8
	v_readlane_b32 s36, v254, 62
	v_lshl_or_b32 v0, v1, 6, v0
	s_add_u32 s26, s36, s26
	v_readlane_b32 s36, v255, 2
	v_lshl_add_u32 v0, v11, 1, v0
	v_mov_b32_e32 v1, v169
	s_addc_u32 s27, s36, s27
	v_lshl_add_u64 v[130:131], s[26:27], 0, v[0:1]
	v_lshlrev_b32_e32 v0, 14, v9
	v_and_b32_e32 v0, 0xffff8000, v0
	s_lshl_b32 s14, s14, 3
	v_lshl_add_u32 v0, v12, 11, v0
	v_and_b32_e32 v1, 1, v9
	s_or_b32 s14, s14, s37
	s_lshl_b32 s15, s15, 5
	v_lshl_or_b32 v0, v1, 6, v0
	s_sub_i32 s14, s14, s15
	v_lshl_add_u32 v0, v13, 1, v0
	v_mov_b32_e32 v1, v169
	s_ashr_i32 s15, s14, 31
	s_waitcnt vmcnt(6)
	v_lshl_add_u64 v[132:133], s[26:27], 0, v[0:1]
	s_lshl_b64 s[14:15], s[14:15], 19
	v_readlane_b32 s26, v254, 58
	s_add_u32 s42, s26, s14
	v_readlane_b32 s14, v254, 54
	v_mov_b32_e32 v0, 0
	v_lshl_or_b32 v136, s93, 6, v134
	s_mov_b32 s60, -2
	s_addc_u32 s43, s14, s15
	s_mov_b64 s[88:89], 0
	v_or_b32_e32 v138, 0x10000, v16
	v_add_u32_e32 v139, 0x10400, v16
	v_add_u32_e32 v140, 0x10800, v16
	v_add_u32_e32 v141, 0x10c00, v16
	v_or_b32_e32 v142, 0x14000, v16
	v_add_u32_e32 v143, 0x14400, v16
	v_add_u32_e32 v144, 0x14800, v16
	v_add_u32_e32 v145, 0x14c00, v16
	s_add_i32 s48, s94, 0xe000
	v_or_b32_e32 v146, 0x18000, v16
	v_add_u32_e32 v147, 0x18400, v16
	v_add_u32_e32 v148, 0x18800, v16
	v_add_u32_e32 v149, 0x18c00, v16
	v_or_b32_e32 v150, 0x1c000, v16
	v_add_u32_e32 v151, 0x1c400, v16
	v_add_u32_e32 v152, 0x1c800, v16
	v_add_u32_e32 v153, 0x1cc00, v16
	v_mov_b32_e32 v1, v0
	v_mov_b32_e32 v2, v0
	v_mov_b32_e32 v3, v0
	v_mov_b32_e32 v4, v0
	v_mov_b32_e32 v5, v0
	v_mov_b32_e32 v6, v0
	v_mov_b32_e32 v7, v0
	v_mov_b32_e32 v8, v0
	v_mov_b32_e32 v9, v0
	v_mov_b32_e32 v10, v0
	v_mov_b32_e32 v11, v0
	v_mov_b32_e32 v12, v0
	v_mov_b32_e32 v13, v0
	v_mov_b32_e32 v14, v0
	v_mov_b32_e32 v15, v0
	v_mov_b32_e32 v16, v0
	v_mov_b32_e32 v17, v0
	v_mov_b32_e32 v18, v0
	v_mov_b32_e32 v19, v0
	v_mov_b32_e32 v20, v0
	v_mov_b32_e32 v21, v0
	v_mov_b32_e32 v22, v0
	v_mov_b32_e32 v23, v0
	v_mov_b32_e32 v24, v0
	v_mov_b32_e32 v25, v0
	v_mov_b32_e32 v26, v0
	v_mov_b32_e32 v27, v0
	v_mov_b32_e32 v28, v0
	v_mov_b32_e32 v29, v0
	v_mov_b32_e32 v30, v0
	v_mov_b32_e32 v31, v0
	v_mov_b32_e32 v32, v0
	v_mov_b32_e32 v33, v0
	v_mov_b32_e32 v34, v0
	v_mov_b32_e32 v35, v0
	v_mov_b32_e32 v36, v0
	v_mov_b32_e32 v37, v0
	v_mov_b32_e32 v38, v0
	v_mov_b32_e32 v39, v0
	v_mov_b32_e32 v40, v0
	v_mov_b32_e32 v41, v0
	v_mov_b32_e32 v42, v0
	v_mov_b32_e32 v43, v0
	v_mov_b32_e32 v48, v0
	v_mov_b32_e32 v49, v0
	v_mov_b32_e32 v50, v0
	v_mov_b32_e32 v51, v0
	v_mov_b32_e32 v56, v0
	v_mov_b32_e32 v57, v0
	v_mov_b32_e32 v58, v0
	v_mov_b32_e32 v59, v0
	v_mov_b32_e32 v60, v0
	v_mov_b32_e32 v61, v0
	v_mov_b32_e32 v62, v0
	v_mov_b32_e32 v63, v0
	v_mov_b32_e32 v64, v0
	v_mov_b32_e32 v65, v0
	v_mov_b32_e32 v66, v0
	v_mov_b32_e32 v67, v0
	v_mov_b32_e32 v68, v0
	v_mov_b32_e32 v69, v0
	v_mov_b32_e32 v70, v0
	v_mov_b32_e32 v71, v0
	v_mov_b32_e32 v44, v0
	v_mov_b32_e32 v45, v0
	v_mov_b32_e32 v46, v0
	v_mov_b32_e32 v47, v0
	v_mov_b32_e32 v52, v0
	v_mov_b32_e32 v53, v0
	v_mov_b32_e32 v54, v0
	v_mov_b32_e32 v55, v0
	v_mov_b32_e32 v80, v0
	v_mov_b32_e32 v81, v0
	v_mov_b32_e32 v82, v0
	v_mov_b32_e32 v83, v0
	v_mov_b32_e32 v84, v0
	v_mov_b32_e32 v85, v0
	v_mov_b32_e32 v86, v0
	v_mov_b32_e32 v87, v0
	v_mov_b32_e32 v88, v0
	v_mov_b32_e32 v89, v0
	v_mov_b32_e32 v90, v0
	v_mov_b32_e32 v91, v0
	v_mov_b32_e32 v92, v0
	v_mov_b32_e32 v93, v0
	v_mov_b32_e32 v94, v0
	v_mov_b32_e32 v95, v0
	v_mov_b32_e32 v96, v0
	v_mov_b32_e32 v97, v0
	v_mov_b32_e32 v98, v0
	v_mov_b32_e32 v99, v0
	v_mov_b32_e32 v100, v0
	v_mov_b32_e32 v101, v0
	v_mov_b32_e32 v102, v0
	v_mov_b32_e32 v103, v0
	v_mov_b32_e32 v72, v0
	v_mov_b32_e32 v73, v0
	v_mov_b32_e32 v74, v0
	v_mov_b32_e32 v75, v0
	v_mov_b32_e32 v76, v0
	v_mov_b32_e32 v77, v0
	v_mov_b32_e32 v78, v0
	v_mov_b32_e32 v79, v0
	v_mov_b32_e32 v104, v0
	v_mov_b32_e32 v105, v0
	v_mov_b32_e32 v106, v0
	v_mov_b32_e32 v107, v0
	v_mov_b32_e32 v108, v0
	v_mov_b32_e32 v109, v0
	v_mov_b32_e32 v110, v0
	v_mov_b32_e32 v111, v0
	v_mov_b32_e32 v112, v0
	v_mov_b32_e32 v113, v0
	v_mov_b32_e32 v114, v0
	v_mov_b32_e32 v115, v0
	v_mov_b32_e32 v116, v0
	v_mov_b32_e32 v117, v0
	v_mov_b32_e32 v118, v0
	v_mov_b32_e32 v119, v0
	v_mov_b32_e32 v120, v0
	v_mov_b32_e32 v121, v0
	v_mov_b32_e32 v122, v0
	v_mov_b32_e32 v123, v0
	v_mov_b32_e32 v124, v0
	v_mov_b32_e32 v125, v0
	v_mov_b32_e32 v126, v0
	v_mov_b32_e32 v127, v0
	s_barrier

.LBB0_75:
	v_mov_b32_e32 v129, v169
	v_and_b32_e32 v134, 48, v3
	v_and_b32_e32 v7, 15, v3
	v_lshlrev_b32_e32 v3, 2, v3
	v_lshl_add_u64 v[12:13], s[16:17], 0, v[168:169]
	v_lshl_add_u64 v[14:15], s[16:17], 0, v[128:129]
	s_and_b32 s16, s24, 3
	v_lshl_or_b32 v135, s26, 6, v7
	v_lshl_or_b32 v7, v7, 6, v134
	v_and_b32_e32 v3, 32, v3
	s_lshl_b32 s17, s26, 13
	v_lshl_add_u64 v[8:9], s[40:41], 0, v[168:169]
	s_lshl_b32 s24, s16, 12
	v_bitop3_b32 v137, v7, s17, v3 bitop3:0xde
	s_add_i32 s17, s90, 0x18000
	v_lshl_add_u64 v[10:11], s[40:41], 0, v[128:129]
	v_bitop3_b32 v136, v7, s24, v3 bitop3:0xde
	v_lshl_add_u64 v[8:9], v[8:9], 0, s[34:35]
	s_mov_b32 m0, s17
	s_add_i32 s24, s90, 0x1a000
	v_lshl_add_u64 v[16:17], s[42:43], 0, v[168:169]
	global_load_lds_dwordx4 v[8:9], off
	v_lshl_add_u64 v[8:9], v[10:11], 0, s[34:35]
	s_mov_b32 m0, s24
	s_add_i32 s60, s90, 0x8000
	v_lshl_add_u64 v[18:19], s[42:43], 0, v[128:129]
	global_load_lds_dwordx4 v[8:9], off
	v_lshl_add_u64 v[8:9], v[16:17], 0, s[34:35]
	s_mov_b32 m0, s60
	s_add_i32 s96, s90, 0xa000
	global_load_lds_dwordx4 v[8:9], off
	v_lshl_add_u64 v[8:9], v[18:19], 0, s[34:35]
	s_mov_b32 m0, s96
	s_add_i32 s97, s90, 0x1c000
	global_load_lds_dwordx4 v[8:9], off
	v_lshl_add_u64 v[8:9], v[12:13], 0, s[34:35]
	s_mov_b32 m0, s97
	s_add_i32 vcc_hi, s90, 0x1e000
	global_load_lds_dwordx4 v[8:9], off
	v_lshl_add_u64 v[8:9], v[14:15], 0, s[34:35]
	s_mov_b32 m0, vcc_hi
	s_lshr_b32 s95, s87, 5
	global_load_lds_dwordx4 v[8:9], off
	s_waitcnt vmcnt(8)
	s_barrier
	v_add_u32_e32 v0, v2, v0
	s_add_u32 s14, s84, s14
	v_add_lshl_u32 v0, v0, v1, 1
	v_mov_b32_e32 v1, v169
	s_addc_u32 s15, s85, s15
	v_lshl_add_u64 v[130:131], s[14:15], 0, v[0:1]
	v_add_u32_e32 v0, v6, v4
	s_waitcnt vmcnt(6)
	v_add_lshl_u32 v0, v0, v5, 1
	v_lshl_add_u64 v[132:133], s[14:15], 0, v[0:1]
	v_mov_b32_e32 v0, 0
	s_mov_b32 s14, 0
	s_mov_b64 s[26:27], 0
	v_mov_b32_e32 v1, v0
	v_mov_b32_e32 v2, v0
	v_mov_b32_e32 v3, v0
	v_mov_b32_e32 v4, v0
	v_mov_b32_e32 v5, v0
	v_mov_b32_e32 v6, v0
	v_mov_b32_e32 v7, v0
	v_mov_b32_e32 v8, v0
	v_mov_b32_e32 v9, v0
	v_mov_b32_e32 v10, v0
	v_mov_b32_e32 v11, v0
	v_mov_b32_e32 v12, v0
	v_mov_b32_e32 v13, v0
	v_mov_b32_e32 v14, v0
	v_mov_b32_e32 v15, v0
	v_mov_b32_e32 v16, v0
	v_mov_b32_e32 v17, v0
	v_mov_b32_e32 v18, v0
	v_mov_b32_e32 v19, v0
	v_mov_b32_e32 v20, v0
	v_mov_b32_e32 v21, v0
	v_mov_b32_e32 v22, v0
	v_mov_b32_e32 v23, v0
	v_mov_b32_e32 v24, v0
	v_mov_b32_e32 v25, v0
	v_mov_b32_e32 v26, v0
	v_mov_b32_e32 v27, v0
	v_mov_b32_e32 v28, v0
	v_mov_b32_e32 v29, v0
	v_mov_b32_e32 v30, v0
	v_mov_b32_e32 v31, v0
	v_mov_b32_e32 v32, v0
	v_mov_b32_e32 v33, v0
	v_mov_b32_e32 v34, v0
	v_mov_b32_e32 v35, v0
	v_mov_b32_e32 v36, v0
	v_mov_b32_e32 v37, v0
	v_mov_b32_e32 v38, v0
	v_mov_b32_e32 v39, v0
	v_mov_b32_e32 v40, v0
	v_mov_b32_e32 v41, v0
	v_mov_b32_e32 v42, v0
	v_mov_b32_e32 v43, v0
	v_mov_b32_e32 v44, v0
	v_mov_b32_e32 v45, v0
	v_mov_b32_e32 v46, v0
	v_mov_b32_e32 v47, v0
	v_mov_b32_e32 v48, v0
	v_mov_b32_e32 v49, v0
	v_mov_b32_e32 v50, v0
	v_mov_b32_e32 v51, v0
	v_mov_b32_e32 v52, v0
	v_mov_b32_e32 v53, v0
	v_mov_b32_e32 v54, v0
	v_mov_b32_e32 v55, v0
	v_mov_b32_e32 v56, v0
	v_mov_b32_e32 v57, v0
	v_mov_b32_e32 v58, v0
	v_mov_b32_e32 v59, v0
	v_mov_b32_e32 v60, v0
	v_mov_b32_e32 v61, v0
	v_mov_b32_e32 v62, v0
	v_mov_b32_e32 v63, v0
	v_mov_b32_e32 v64, v0
	v_mov_b32_e32 v65, v0
	v_mov_b32_e32 v66, v0
	v_mov_b32_e32 v67, v0
	v_mov_b32_e32 v68, v0
	v_mov_b32_e32 v69, v0
	v_mov_b32_e32 v70, v0
	v_mov_b32_e32 v71, v0
	v_mov_b32_e32 v72, v0
	v_mov_b32_e32 v73, v0
	v_mov_b32_e32 v74, v0
	v_mov_b32_e32 v75, v0
	v_mov_b32_e32 v76, v0
	v_mov_b32_e32 v77, v0
	v_mov_b32_e32 v78, v0
	v_mov_b32_e32 v79, v0
	v_mov_b32_e32 v80, v0
	v_mov_b32_e32 v81, v0
	v_mov_b32_e32 v82, v0
	v_mov_b32_e32 v83, v0
	v_mov_b32_e32 v84, v0
	v_mov_b32_e32 v85, v0
	v_mov_b32_e32 v86, v0
	v_mov_b32_e32 v87, v0
	v_mov_b32_e32 v88, v0
	v_mov_b32_e32 v89, v0
	v_mov_b32_e32 v90, v0
	v_mov_b32_e32 v91, v0
	v_mov_b32_e32 v92, v0
	v_mov_b32_e32 v93, v0
	v_mov_b32_e32 v94, v0
	v_mov_b32_e32 v95, v0
	v_mov_b32_e32 v96, v0
	v_mov_b32_e32 v97, v0
	v_mov_b32_e32 v98, v0
	v_mov_b32_e32 v99, v0
	v_mov_b32_e32 v100, v0
	v_mov_b32_e32 v101, v0
	v_mov_b32_e32 v102, v0
	v_mov_b32_e32 v103, v0
	v_mov_b32_e32 v104, v0
	v_mov_b32_e32 v105, v0
	v_mov_b32_e32 v106, v0
	v_mov_b32_e32 v107, v0
	v_mov_b32_e32 v108, v0
	v_mov_b32_e32 v109, v0
	v_mov_b32_e32 v110, v0
	v_mov_b32_e32 v111, v0
	v_mov_b32_e32 v112, v0
	v_mov_b32_e32 v113, v0
	v_mov_b32_e32 v114, v0
	v_mov_b32_e32 v115, v0
	v_mov_b32_e32 v116, v0
	v_mov_b32_e32 v117, v0
	v_mov_b32_e32 v118, v0
	v_mov_b32_e32 v119, v0
	v_mov_b32_e32 v120, v0
	v_mov_b32_e32 v121, v0
	v_mov_b32_e32 v122, v0
	v_mov_b32_e32 v123, v0
	v_mov_b32_e32 v124, v0
	v_mov_b32_e32 v125, v0
	v_mov_b32_e32 v126, v0
	v_mov_b32_e32 v127, v0
	s_barrier

.LBB0_209:
	s_and_b32 s55, s24, 3
	v_and_b32_e32 v7, 15, v6
	v_and_b32_e32 v135, 48, v6
	v_lshlrev_b32_e32 v6, 2, v6
	v_lshl_add_u64 v[8:9], s[40:41], 0, v[168:169]
	v_mov_b32_e32 v129, v169
	v_lshl_or_b32 v134, s27, 6, v7
	v_lshl_or_b32 v7, v7, 6, v135
	v_and_b32_e32 v6, 32, v6
	s_lshl_b32 s24, s27, 13
	s_lshl_b32 s27, s55, 12
	s_add_i32 s56, s16, 0x18000
	v_lshl_add_u64 v[10:11], s[40:41], 0, v[128:129]
	v_bitop3_b32 v136, v7, s27, v6 bitop3:0xde
	v_bitop3_b32 v137, v7, s24, v6 bitop3:0xde
	v_lshl_add_u64 v[6:7], v[8:9], 0, s[34:35]
	s_mov_b32 m0, s56
	s_add_i32 s85, s16, 0x1a000
	v_lshl_add_u64 v[12:13], s[42:43], 0, v[168:169]
	s_and_b32 s57, s62, 7
	global_load_lds_dwordx4 v[6:7], off
	v_lshl_add_u64 v[6:7], v[10:11], 0, s[34:35]
	s_mov_b32 m0, s85
	s_add_i32 s86, s16, 0x8000
	s_add_i32 s87, s16, 0xa000
	v_lshl_add_u64 v[14:15], s[42:43], 0, v[128:129]
	global_load_lds_dwordx4 v[6:7], off
	v_lshl_add_u64 v[6:7], v[12:13], 0, s[34:35]
	s_mov_b32 m0, s86
	s_add_u32 s36, s40, 0x40080
	global_load_lds_dwordx4 v[6:7], off
	v_lshl_add_u64 v[6:7], v[14:15], 0, s[34:35]
	s_mov_b32 m0, s87
	s_addc_u32 s37, s41, 0
	s_add_i32 s90, s16, 0x1c000
	global_load_lds_dwordx4 v[6:7], off
	v_lshl_add_u64 v[6:7], s[36:37], 0, v[168:169]
	s_mov_b32 m0, s90
	s_add_i32 s24, s16, 0x1e000
	global_load_lds_dwordx4 v[6:7], off
	v_lshl_add_u64 v[6:7], s[36:37], 0, v[128:129]
	s_mov_b32 m0, s24
	s_add_i32 s26, s26, s57
	global_load_lds_dwordx4 v[6:7], off
	s_waitcnt vmcnt(8)
	s_barrier
	s_ashr_i32 s27, s26, 31
	s_lshl_b64 s[26:27], s[26:27], 19
	v_lshlrev_b32_e32 v6, 14, v0
	s_add_u32 s60, s74, s26
	v_and_b32_e32 v6, 0xffff8000, v6
	s_addc_u32 s91, s75, s27
	v_lshl_add_u32 v1, v1, 11, v6
	v_and_b32_e32 v0, 1, v0
	v_lshl_or_b32 v0, v0, 6, v1
	s_add_u32 s26, s18, s26
	v_lshl_add_u32 v0, v3, 1, v0
	v_mov_b32_e32 v1, v169
	s_addc_u32 s27, s19, s27
	v_lshl_add_u64 v[130:131], s[26:27], 0, v[0:1]
	v_lshlrev_b32_e32 v0, 14, v2
	v_and_b32_e32 v0, 0xffff8000, v0
	v_lshl_add_u32 v0, v4, 11, v0
	v_and_b32_e32 v1, 1, v2
	v_lshl_or_b32 v0, v1, 6, v0
	s_waitcnt vmcnt(6)
	v_lshl_add_u32 v0, v5, 1, v0
	v_mov_b32_e32 v1, v169
	v_lshl_add_u64 v[132:133], s[26:27], 0, v[0:1]
	s_add_u32 s92, s30, s14
	v_mov_b32_e32 v0, 0
	s_addc_u32 s93, s61, s15
	s_mov_b32 s94, -2
	s_mov_b64 s[44:45], 0
	v_mov_b32_e32 v1, v0
	v_mov_b32_e32 v2, v0
	v_mov_b32_e32 v3, v0
	v_mov_b32_e32 v4, v0
	v_mov_b32_e32 v5, v0
	v_mov_b32_e32 v6, v0
	v_mov_b32_e32 v7, v0
	v_mov_b32_e32 v8, v0
	v_mov_b32_e32 v9, v0
	v_mov_b32_e32 v10, v0
	v_mov_b32_e32 v11, v0
	v_mov_b32_e32 v12, v0
	v_mov_b32_e32 v13, v0
	v_mov_b32_e32 v14, v0
	v_mov_b32_e32 v15, v0
	v_mov_b32_e32 v16, v0
	v_mov_b32_e32 v17, v0
	v_mov_b32_e32 v18, v0
	v_mov_b32_e32 v19, v0
	v_mov_b32_e32 v20, v0
	v_mov_b32_e32 v21, v0
	v_mov_b32_e32 v22, v0
	v_mov_b32_e32 v23, v0
	v_mov_b32_e32 v24, v0
	v_mov_b32_e32 v25, v0
	v_mov_b32_e32 v26, v0
	v_mov_b32_e32 v27, v0
	v_mov_b32_e32 v28, v0
	v_mov_b32_e32 v29, v0
	v_mov_b32_e32 v30, v0
	v_mov_b32_e32 v31, v0
	v_mov_b32_e32 v32, v0
	v_mov_b32_e32 v33, v0
	v_mov_b32_e32 v34, v0
	v_mov_b32_e32 v35, v0
	v_mov_b32_e32 v36, v0
	v_mov_b32_e32 v37, v0
	v_mov_b32_e32 v38, v0
	v_mov_b32_e32 v39, v0
	v_mov_b32_e32 v40, v0
	v_mov_b32_e32 v41, v0
	v_mov_b32_e32 v42, v0
	v_mov_b32_e32 v43, v0
	v_mov_b32_e32 v44, v0
	v_mov_b32_e32 v45, v0
	v_mov_b32_e32 v46, v0
	v_mov_b32_e32 v47, v0
	v_mov_b32_e32 v48, v0
	v_mov_b32_e32 v49, v0
	v_mov_b32_e32 v50, v0
	v_mov_b32_e32 v51, v0
	v_mov_b32_e32 v52, v0
	v_mov_b32_e32 v53, v0
	v_mov_b32_e32 v54, v0
	v_mov_b32_e32 v55, v0
	v_mov_b32_e32 v56, v0
	v_mov_b32_e32 v57, v0
	v_mov_b32_e32 v58, v0
	v_mov_b32_e32 v59, v0
	v_mov_b32_e32 v60, v0
	v_mov_b32_e32 v61, v0
	v_mov_b32_e32 v62, v0
	v_mov_b32_e32 v63, v0
	v_mov_b32_e32 v64, v0
	v_mov_b32_e32 v65, v0
	v_mov_b32_e32 v66, v0
	v_mov_b32_e32 v67, v0
	v_mov_b32_e32 v68, v0
	v_mov_b32_e32 v69, v0
	v_mov_b32_e32 v70, v0
	v_mov_b32_e32 v71, v0
	v_mov_b32_e32 v72, v0
	v_mov_b32_e32 v73, v0
	v_mov_b32_e32 v74, v0
	v_mov_b32_e32 v75, v0
	v_mov_b32_e32 v76, v0
	v_mov_b32_e32 v77, v0
	v_mov_b32_e32 v78, v0
	v_mov_b32_e32 v79, v0
	v_mov_b32_e32 v80, v0
	v_mov_b32_e32 v81, v0
	v_mov_b32_e32 v82, v0
	v_mov_b32_e32 v83, v0
	v_mov_b32_e32 v84, v0
	v_mov_b32_e32 v85, v0
	v_mov_b32_e32 v86, v0
	v_mov_b32_e32 v87, v0
	v_mov_b32_e32 v88, v0
	v_mov_b32_e32 v89, v0
	v_mov_b32_e32 v90, v0
	v_mov_b32_e32 v91, v0
	v_mov_b32_e32 v92, v0
	v_mov_b32_e32 v93, v0
	v_mov_b32_e32 v94, v0
	v_mov_b32_e32 v95, v0
	v_mov_b32_e32 v96, v0
	v_mov_b32_e32 v97, v0
	v_mov_b32_e32 v98, v0
	v_mov_b32_e32 v99, v0
	v_mov_b32_e32 v100, v0
	v_mov_b32_e32 v101, v0
	v_mov_b32_e32 v102, v0
	v_mov_b32_e32 v103, v0
	v_mov_b32_e32 v104, v0
	v_mov_b32_e32 v105, v0
	v_mov_b32_e32 v106, v0
	v_mov_b32_e32 v107, v0
	v_mov_b32_e32 v108, v0
	v_mov_b32_e32 v109, v0
	v_mov_b32_e32 v110, v0
	v_mov_b32_e32 v111, v0
	v_mov_b32_e32 v112, v0
	v_mov_b32_e32 v113, v0
	v_mov_b32_e32 v114, v0
	v_mov_b32_e32 v115, v0
	v_mov_b32_e32 v116, v0
	v_mov_b32_e32 v117, v0
	v_mov_b32_e32 v118, v0
	v_mov_b32_e32 v119, v0
	v_mov_b32_e32 v120, v0
	v_mov_b32_e32 v121, v0
	v_mov_b32_e32 v122, v0
	v_mov_b32_e32 v123, v0
	v_mov_b32_e32 v124, v0
	v_mov_b32_e32 v125, v0
	v_mov_b32_e32 v126, v0
	v_mov_b32_e32 v127, v0
	s_nop 0
	s_nop 0
	s_nop 0
	s_nop 0
	s_nop 0
	s_nop 0
	s_nop 0
	s_nop 0
	s_nop 0
	s_nop 0
	s_nop 0
	s_nop 0
	s_nop 0
	s_nop 0
	s_nop 0
	s_barrier
